# unswizzled P4 LDS image; unit-start vmcnt(0) drains removed in P5/P6/P7/P9
# baseline (speedup 1.0000x reference)
; __device__ __forceinline__ void p4_attn(const Params& p, unsigned char* lds, int bid, int nb, bool dry) {
;     ...
;   const int tok = wid >> 1, hw = wid & 1, head = hw * 16 + r16;
;   const float SC = 0.08838834764831845f * LOG2E;
;   const int qoff = 16 * (g ^ (r16 >> 3));
;   const int q4 = r16 >> 2, pp = r16 & 3;
;   const int troff = (4 * g + q4) * CROW + 16 * ((pp >> 1) ^ (g >> 1)) + 8 * (pp & 1);
;   const int wrow = 16 * hw + 8 * (lane >> 5), wch = lane & 31;
.LBB0_988:
	s_or_b64 exec, exec, s[4:5]
	v_cmp_gt_i32_e32 vcc, 4, v2
	s_and_saveexec_b64 s[4:5], vcc
	v_add_u32_e32 v0, 0x26880, v0
	v_mov_b32_e32 v1, 0
	ds_write_b32 v0, v1
	s_or_b64 exec, exec, s[4:5]
	v_bfe_u32 v5, v2, 4, 2
	v_bfe_u32 v0, v2, 3, 1
	v_mov_b32_e32 v0, v5
	v_lshlrev_b32_e32 v162, 4, v0
	v_bfe_u32 v0, v2, 2, 2
	v_lshlrev_b32_e32 v148, 2, v5
	v_or_b32_e32 v0, v148, v0
	s_ashr_i32 s0, s3, 7
	s_lshr_b32 s3, s3, 2
	v_mul_u32_u24_e32 v163, 0x220, v0
	v_lshrrev_b32_e32 v0, 1, v2
	v_bfe_u32 v8, v2, 5, 1
	v_and_b32_e32 v6, 15, v2
	s_and_b32 s3, s3, 16
	v_and_b32_e32 v0, 1, v0
	v_readlane_b32 s4, v254, 36
	v_or_b32_e32 v7, s3, v6
	v_lshlrev_b32_e32 v164, 4, v0
	v_lshlrev_b32_e32 v0, 3, v2
	v_ashrrev_i32_e32 v3, 31, v2
	v_readlane_b32 s5, v254, 37
	v_and_b32_e32 v165, 8, v0
	v_and_b32_e32 v10, 31, v2
	v_lshl_add_u64 v[150:151], v[2:3], 2, s[4:5]
	v_lshlrev_b32_e32 v0, 8, v7
	v_mov_b32_e32 v1, 0
	v_readlane_b32 s4, v254, 42
	v_lshl_add_u64 v[152:153], s[92:93], 0, v[0:1]
	v_lshlrev_b32_e32 v0, 4, v10
	v_readlane_b32 s5, v254, 43
	v_lshl_or_b32 v9, v8, 3, s3
	s_add_i32 s3, 0, 0x26080
	v_lshl_add_u64 v[156:157], s[4:5], 0, v[0:1]
	s_lshl_b32 s4, s0, 9
	s_lshl_b32 s2, s0, 2
	v_lshl_add_u32 v166, v2, 2, s3
	s_add_i32 s3, s3, s4
	s_mul_i32 s4, s0, 0x4400
	v_and_b32_e32 v0, 31, v2
	s_add_i32 s2, s2, 0
	v_and_b32_e32 v4, 63, v2
	s_add_i32 s5, s4, 0
	v_lshlrev_b32_e32 v0, 4, v0
	s_add_i32 s4, 0, 0x22000
	v_mul_u32_u24_e32 v2, 0x220, v9
	s_mov_b32 s1, 0
	s_add_i32 s2, s2, 0x26880
	v_lshlrev_b32_e32 v154, 3, v5
	v_mov_b32_e32 v155, v1
	v_cmp_eq_u32_e64 s[8:9], 0, v4
	v_lshl_add_u32 v167, v9, 1, s3
	v_mul_u32_u24_e32 v168, 0x220, v6
	v_lshl_add_u32 v169, v7, 2, s4
	v_mov_b32_e32 v149, v1
	v_add3_u32 v170, s5, v0, v2
	s_movk_i32 s16, 0x80
	s_mov_b32 s4, 0x3e0293ee
	s_mov_b32 s17, 0xf149f2ca
	s_mov_b32 s18, 0x41800000
	v_mov_b32_e32 v171, 9
	v_mov_b32_e32 v172, 0x80
	v_mov_b32_e32 v173, 0xf149f2ca
	s_mov_b32 s10, 0
	s_mov_b32 s19, 0
	s_mov_b32 s20, 0
	s_lshl_b32 s28, s88, 11
	s_mov_b32 s29, 0
	v_lshl_add_u64 v[2:3], v[150:151], 0, s[28:29]
	global_load_dword v255, v[2:3], off
	s_waitcnt vmcnt(0)
	s_waitcnt lgkmcnt(0)
	s_barrier

; #define G8_STAGE(bufoff, gbase, NM) do { _Pragma("unroll") for (int _i = 0; _i < 2; ++_i) { \
;     const char* _b = (const char*)(gbase) + (_i ? p2##NM : (size_t)0); asm volatile("" : "+s"(_b));     \
;     __builtin_amdgcn_global_load_lds((const unsigned*)(_b + voff##NM), (LAS unsigned*)(lds + (bufoff) + ldsw + _i * 8192), 16, 0, 0); } } while (0)
; #define G8_WAIT_V(n) asm volatile("s_waitcnt vmcnt(" #n ")" ::: "memory")
; #define G8_WAIT_L(n) asm volatile("s_waitcnt lgkmcnt(" #n ")" ::: "memory")
; #define G8_BAR __builtin_amdgcn_s_barrier()
; #define G8_SCHED __builtin_amdgcn_sched_barrier(0)
;     ...
;       G8_LDB(B0, 0, 0); G8_LDB(B1, 0, 1); G8_SCHED; G8_LDA(At, 0, 0); G8_STAGE(G8_SA(1, 1), a1, A);
;       const bool d0a = (BD == 0) || (BD == 1 && t < (nt >> 1)) || (BD == 2 && !(cur.pn & 1));
;       const bool d1a = (BD == 0) || (BD == 1 && t >= (nt >> 1)) || (BD == 2 && !(cur.pn & 1));
;       const bool d0b = (BD == 0) || (BD == 1 && t < (nt >> 1)) || (BD == 2 && (cur.pn & 1));
;       const bool d1b = (BD == 0) || (BD == 1 && t >= (nt >> 1)) || (BD == 2 && (cur.pn & 1));
;       G8_WAIT_V(8); G8_WAIT_L(0); G8_BAR; if (d0a) G8_MMA(0, 0, At, B0); if (d1a) G8_MMA(0, 1, At, B1); G8_BAR; G8_SCHED;
.LBB0_1045:
	s_add_u32 s48, s30, 0x100080
	s_addc_u32 s49, s31, 0
	s_add_u32 s38, s30, 0x100
	s_addc_u32 s39, s31, 0
	s_add_u32 s40, s36, 0x100
	s_addc_u32 s41, s37, 0
	s_add_u32 s34, s30, 0x180
	s_addc_u32 s35, s31, 0
	s_add_u32 s36, s36, 0x180
	s_addc_u32 s37, s37, 0
	ds_read_b128 v[0:3], v139
	ds_read_b128 v[4:7], v139 offset:1024
	ds_read_b128 v[8:11], v139 offset:2048
	ds_read_b128 v[12:15], v139 offset:3072
	s_mov_b64 s[50:51], s[48:49]
	ds_read_b128 v[16:19], v140
	ds_read_b128 v[20:23], v140 offset:1024
	ds_read_b128 v[24:27], v140 offset:2048
	ds_read_b128 v[28:31], v140 offset:3072
	ds_read_b128 v[32:35], v140 offset:4096
	ds_read_b128 v[36:39], v140 offset:5120
	ds_read_b128 v[40:43], v140 offset:6144
	ds_read_b128 v[44:47], v140 offset:7168
	s_nop 0
	v_lshl_add_u64 v[48:49], s[50:51], 0, v[128:129]
	s_add_i32 s51, s1, 0xc000
	s_add_u32 s48, s48, 0x80000
	s_mov_b32 m0, s51
	s_addc_u32 s49, s49, 0
	s_add_i32 s23, s1, 0xe000
	global_load_lds_dwordx4 v[48:49], off
	s_mov_b32 m0, s23
	v_lshl_add_u64 v[48:49], s[48:49], 0, v[128:129]
	global_load_lds_dwordx4 v[48:49], off
	s_waitcnt vmcnt(8)
	s_waitcnt lgkmcnt(0)
	s_barrier
	s_setprio 1
	s_waitcnt lgkmcnt(0)
	v_mfma_f32_16x16x128_f8f6f4 v[48:51], v[0:7], v[16:23], 0
	v_mfma_f32_16x16x128_f8f6f4 v[52:55], v[8:15], v[16:23], 0
	v_mfma_f32_16x16x128_f8f6f4 v[56:59], v[0:7], v[24:31], 0
	v_mfma_f32_16x16x128_f8f6f4 v[60:63], v[8:15], v[24:31], 0
	v_mfma_f32_16x16x128_f8f6f4 v[64:67], v[0:7], v[32:39], 0
	v_mfma_f32_16x16x128_f8f6f4 v[68:71], v[8:15], v[32:39], 0
	v_mfma_f32_16x16x128_f8f6f4 v[80:83], v[0:7], v[40:47], 0
	v_mfma_f32_16x16x128_f8f6f4 v[84:87], v[8:15], v[40:47], 0
	s_setprio 0
	s_barrier
	s_mov_b64 s[48:49], s[40:41]
	ds_read_b128 v[16:19], v140 offset:16384
	ds_read_b128 v[20:23], v140 offset:17408
	ds_read_b128 v[24:27], v140 offset:18432
	ds_read_b128 v[28:31], v140 offset:19456
	ds_read_b128 v[32:35], v140 offset:20480
	ds_read_b128 v[36:39], v140 offset:21504
	ds_read_b128 v[40:43], v140 offset:22528
	ds_read_b128 v[44:47], v140 offset:23552
	s_add_i32 s52, s43, s0
	v_lshl_add_u64 v[72:73], s[48:49], 0, v[130:131]
	s_add_u32 s48, s40, 0x8000
	s_mov_b32 m0, s52
	s_addc_u32 s49, s41, 0
	global_load_lds_dwordx4 v[72:73], off
	s_add_i32 s47, s52, 0x2000
	v_lshl_add_u64 v[72:73], s[48:49], 0, v[130:131]
	s_add_u32 s48, s40, 0x10000
	s_mov_b32 m0, s47
	s_addc_u32 s49, s41, 0
	global_load_lds_dwordx4 v[72:73], off
	s_mov_b64 s[54:55], s[38:39]
	v_lshl_add_u64 v[72:73], s[48:49], 0, v[130:131]
	s_add_i32 s48, s44, s0
	s_add_u32 s40, s40, 0x18000
	s_mov_b32 m0, s48
	s_addc_u32 s41, s41, 0
	global_load_lds_dwordx4 v[72:73], off
	s_nop 0
	v_lshl_add_u64 v[72:73], s[40:41], 0, v[130:131]
	s_add_i32 s40, s48, 0x2000
	s_mov_b32 m0, s40
	s_nop 0
	global_load_lds_dwordx4 v[72:73], off
	s_mov_b32 m0, s1
	v_lshl_add_u64 v[72:73], s[54:55], 0, v[128:129]
	s_add_u32 s54, s38, 0x80000
	s_addc_u32 s55, s39, 0
	global_load_lds_dwordx4 v[72:73], off
	s_mov_b32 m0, s2
	v_lshl_add_u64 v[72:73], s[54:55], 0, v[128:129]
	global_load_lds_dwordx4 v[72:73], off
	s_waitcnt vmcnt(8)
	s_waitcnt lgkmcnt(0)
	s_barrier
	s_setprio 1
	s_waitcnt lgkmcnt(0)
	v_mfma_f32_16x16x128_f8f6f4 v[96:99], v[0:7], v[16:23], 0
	v_mfma_f32_16x16x128_f8f6f4 v[100:103], v[8:15], v[16:23], 0
	v_mfma_f32_16x16x128_f8f6f4 v[112:115], v[0:7], v[24:31], 0
	v_mfma_f32_16x16x128_f8f6f4 v[116:119], v[8:15], v[24:31], 0
	v_mfma_f32_16x16x128_f8f6f4 v[120:123], v[0:7], v[32:39], 0
	v_mfma_f32_16x16x128_f8f6f4 v[124:127], v[8:15], v[32:39], 0
	v_mfma_f32_16x16x128_f8f6f4 v[132:135], v[0:7], v[40:47], 0
	v_mfma_f32_16x16x128_f8f6f4 v[142:145], v[8:15], v[40:47], 0
	s_setprio 0
	s_barrier
	s_add_i32 s53, 0, 0x18000
	v_add_u32_e32 v8, s53, v138
	ds_read_b128 v[0:3], v8
	ds_read_b128 v[4:7], v8 offset:1024
	ds_read_b128 v[16:19], v8 offset:2048
	ds_read_b128 v[20:23], v8 offset:3072
	s_add_u32 s54, s38, 0x100000
	s_addc_u32 s55, s39, 0
	s_add_u32 s38, s38, 0x180000
	s_mov_b32 m0, s3
	ds_read_b128 v[8:11], v140 offset:32768
	ds_read_b128 v[12:15], v140 offset:33792
	ds_read_b128 v[24:27], v140 offset:34816
	ds_read_b128 v[28:31], v140 offset:35840
	ds_read_b128 v[32:35], v140 offset:36864
	ds_read_b128 v[36:39], v140 offset:37888
	ds_read_b128 v[40:43], v140 offset:38912
	ds_read_b128 v[44:47], v140 offset:39936
	s_addc_u32 s39, s39, 0
	v_lshl_add_u64 v[72:73], s[54:55], 0, v[128:129]
	global_load_lds_dwordx4 v[72:73], off
	s_mov_b32 m0, s13
	v_lshl_add_u64 v[72:73], s[38:39], 0, v[128:129]
	global_load_lds_dwordx4 v[72:73], off
	s_waitcnt vmcnt(8)
	s_waitcnt lgkmcnt(0)
	s_barrier
	s_setprio 1
	s_waitcnt lgkmcnt(0)
	v_mfma_f32_16x16x128_f8f6f4 v[108:111], v[0:7], v[8:15], v[48:51]
	v_mfma_f32_16x16x128_f8f6f4 v[104:107], v[16:23], v[8:15], v[52:55]
	v_mfma_f32_16x16x128_f8f6f4 v[92:95], v[0:7], v[24:31], v[56:59]
	v_mfma_f32_16x16x128_f8f6f4 v[88:91], v[16:23], v[24:31], v[60:63]
	v_mfma_f32_16x16x128_f8f6f4 v[76:79], v[0:7], v[32:39], v[64:67]
	v_mfma_f32_16x16x128_f8f6f4 v[72:75], v[16:23], v[32:39], v[68:71]
	v_mfma_f32_16x16x128_f8f6f4 v[60:63], v[0:7], v[40:47], v[80:83]
	v_mfma_f32_16x16x128_f8f6f4 v[56:59], v[16:23], v[40:47], v[84:87]
	s_setprio 0
	s_barrier
; #define G8_STAGE(bufoff, gbase, NM) do { _Pragma("unroll") for (int _i = 0; _i < 2; ++_i) { \
;     const char* _b = (const char*)(gbase) + (_i ? p2##NM : (size_t)0); asm volatile("" : "+s"(_b));     \
;     __builtin_amdgcn_global_load_lds((const unsigned*)(_b + voff##NM), (LAS unsigned*)(lds + (bufoff) + ldsw + _i * 8192), 16, 0, 0); } } while (0)
; #define G8_WAIT_V(n) asm volatile("s_waitcnt vmcnt(" #n ")" ::: "memory")
; #define G8_WAIT_L(n) asm volatile("s_waitcnt lgkmcnt(" #n ")" ::: "memory")
; #define G8_BAR __builtin_amdgcn_s_barrier()
; #define G8_SCHED __builtin_amdgcn_sched_barrier(0)
;     ...
;       G8_LDA(At, 0, 1); G8_STAGE(G8_SB(0, 0), b2, B); G8_STAGE(G8_SB(0, 1), b2 + hstepB, B); G8_STAGE(G8_SA(0, 0), a2, A);
;       G8_WAIT_V(8); G8_WAIT_L(0); G8_BAR; if (d0a) G8_MMA(1, 0, At, B0); if (d1a) G8_MMA(1, 1, At, B1); G8_BAR; G8_SCHED;
;       G8_LDB(B0, 1, 0); G8_LDB(B1, 1, 1); G8_SCHED; G8_LDA(At, 1, 0); G8_STAGE(G8_SA(0, 1), a2 + hstepA, A);
;       G8_WAIT_V(8); G8_WAIT_L(0); G8_BAR; if (d0b) G8_MMA(0, 0, At, B0); if (d1b) G8_MMA(0, 1, At, B1); G8_BAR; G8_SCHED;
;       G8_LDA(At, 1, 1); G8_STAGE(G8_SB(1, 0), b3, B); G8_STAGE(G8_SB(1, 1), b3 + hstepB, B); G8_STAGE(G8_SA(1, 0), a3, A);
;       G8_WAIT_V(8); G8_WAIT_L(0); G8_BAR; if (d0b) G8_MMA(1, 0, At, B0); if (d1b) G8_MMA(1, 1, At, B1); G8_BAR; G8_SCHED;
	s_mov_b64 s[38:39], s[36:37]
	ds_read_b128 v[8:11], v140 offset:49152
	ds_read_b128 v[12:15], v140 offset:50176
	ds_read_b128 v[32:35], v140 offset:51200
	ds_read_b128 v[36:39], v140 offset:52224
	ds_read_b128 v[48:51], v140 offset:53248
	ds_read_b128 v[52:55], v140 offset:54272
	ds_read_b128 v[64:67], v140 offset:55296
	ds_read_b128 v[68:71], v140 offset:56320
	s_add_i32 s53, s53, s0
	v_lshl_add_u64 v[24:25], s[38:39], 0, v[130:131]
	s_add_u32 s38, s36, 0x8000
	s_mov_b32 m0, s53
	s_addc_u32 s39, s37, 0
	global_load_lds_dwordx4 v[24:25], off
	s_add_i32 s41, s53, 0x2000
	v_lshl_add_u64 v[24:25], s[38:39], 0, v[130:131]
	s_add_u32 s38, s36, 0x10000
	s_addc_u32 s39, s37, 0
	s_add_i32 s54, 0, 0x1c000
	s_add_i32 s49, s54, s0
	s_mov_b32 m0, s41
	s_add_u32 s36, s36, 0x18000
	global_load_lds_dwordx4 v[24:25], off
	s_mov_b32 m0, s49
	v_lshl_add_u64 v[24:25], s[38:39], 0, v[130:131]
	s_addc_u32 s37, s37, 0
	global_load_lds_dwordx4 v[24:25], off
	s_add_i32 s50, s49, 0x2000
	v_lshl_add_u64 v[24:25], s[36:37], 0, v[130:131]
	s_mov_b32 m0, s50
	s_mov_b64 s[36:37], s[34:35]
	s_add_u32 s34, s34, 0x80000
	global_load_lds_dwordx4 v[24:25], off
	s_mov_b32 m0, s29
	v_lshl_add_u64 v[24:25], s[36:37], 0, v[128:129]
	s_addc_u32 s35, s35, 0
	global_load_lds_dwordx4 v[24:25], off
	s_mov_b32 m0, s33
	v_lshl_add_u64 v[24:25], s[34:35], 0, v[128:129]
	global_load_lds_dwordx4 v[24:25], off
	s_waitcnt vmcnt(8)
	s_waitcnt lgkmcnt(0)
	s_barrier
	s_setprio 1
	s_waitcnt lgkmcnt(0)
	v_mfma_f32_16x16x128_f8f6f4 v[44:47], v[0:7], v[8:15], v[96:99]
	v_mfma_f32_16x16x128_f8f6f4 v[40:43], v[16:23], v[8:15], v[100:103]
	v_mfma_f32_16x16x128_f8f6f4 v[28:31], v[0:7], v[32:39], v[112:115]
	v_mfma_f32_16x16x128_f8f6f4 v[24:27], v[16:23], v[32:39], v[116:119]
	v_mfma_f32_16x16x128_f8f6f4 v[12:15], v[0:7], v[48:55], v[120:123]
	v_mfma_f32_16x16x128_f8f6f4 v[8:11], v[16:23], v[48:55], v[124:127]
	v_mfma_f32_16x16x128_f8f6f4 v[4:7], v[0:7], v[64:71], v[132:135]
	v_mfma_f32_16x16x128_f8f6f4 v[0:3], v[16:23], v[64:71], v[142:145]
	s_setprio 0
	s_barrier
	s_add_u32 s56, s30, 0x100180
	s_addc_u32 s57, s31, 0
	s_add_u32 s30, s24, 0x80
	s_addc_u32 s31, s25, 0
	s_add_u32 s34, s26, 0x80
	s_addc_u32 s35, s27, 0
	s_mov_b64 s[38:39], s[26:27]
	s_mov_b64 s[36:37], s[24:25]
	ds_read_b128 v[16:19], v141
	ds_read_b128 v[20:23], v141 offset:1024
	ds_read_b128 v[32:35], v141 offset:2048
	ds_read_b128 v[36:39], v141 offset:3072
	s_mov_b64 s[58:59], s[56:57]
	s_add_u32 s56, s56, 0x80000
	s_mov_b32 m0, s51
	ds_read_b128 v[48:51], v140
	ds_read_b128 v[52:55], v140 offset:1024
	ds_read_b128 v[64:67], v140 offset:2048
	ds_read_b128 v[68:71], v140 offset:3072
	ds_read_b128 v[80:83], v140 offset:4096
	ds_read_b128 v[84:87], v140 offset:5120
	ds_read_b128 v[96:99], v140 offset:6144
	ds_read_b128 v[100:103], v140 offset:7168
	s_addc_u32 s57, s57, 0
	v_lshl_add_u64 v[112:113], s[58:59], 0, v[128:129]
	global_load_lds_dwordx4 v[112:113], off
	s_mov_b32 m0, s23
	v_lshl_add_u64 v[112:113], s[56:57], 0, v[128:129]
	global_load_lds_dwordx4 v[112:113], off
	s_waitcnt vmcnt(8)
	s_waitcnt lgkmcnt(0)
	s_barrier
	s_setprio 1
	s_waitcnt lgkmcnt(0)
	v_mfma_f32_16x16x128_f8f6f4 v[112:115], v[16:23], v[48:55], 0
	v_mfma_f32_16x16x128_f8f6f4 v[116:119], v[32:39], v[48:55], 0
	v_mfma_f32_16x16x128_f8f6f4 v[132:135], v[16:23], v[64:71], 0
	v_mfma_f32_16x16x128_f8f6f4 v[158:161], v[32:39], v[64:71], 0
	v_mfma_f32_16x16x128_f8f6f4 v[162:165], v[16:23], v[80:87], 0
	v_mfma_f32_16x16x128_f8f6f4 v[166:169], v[32:39], v[80:87], 0
	v_mfma_f32_16x16x128_f8f6f4 v[170:173], v[16:23], v[96:103], 0
	v_mfma_f32_16x16x128_f8f6f4 v[174:177], v[32:39], v[96:103], 0
	s_setprio 0
	s_barrier
	s_mov_b64 s[56:57], s[38:39]
	ds_read_b128 v[48:51], v140 offset:16384
	ds_read_b128 v[52:55], v140 offset:17408
	ds_read_b128 v[64:67], v140 offset:18432
	ds_read_b128 v[68:71], v140 offset:19456
	ds_read_b128 v[80:83], v140 offset:20480
	ds_read_b128 v[84:87], v140 offset:21504
	ds_read_b128 v[96:99], v140 offset:22528
	ds_read_b128 v[100:103], v140 offset:23552
	s_mov_b32 m0, s52
	v_lshl_add_u64 v[120:121], s[56:57], 0, v[130:131]
	s_add_u32 s56, s38, 0x8000
	s_addc_u32 s57, s39, 0
	global_load_lds_dwordx4 v[120:121], off
	s_mov_b32 m0, s47
	v_lshl_add_u64 v[120:121], s[56:57], 0, v[130:131]
	s_add_u32 s56, s38, 0x10000
	s_addc_u32 s57, s39, 0
	s_add_u32 s38, s38, 0x18000
	global_load_lds_dwordx4 v[120:121], off
	s_mov_b32 m0, s48
	v_lshl_add_u64 v[120:121], s[56:57], 0, v[130:131]
	s_addc_u32 s39, s39, 0
	global_load_lds_dwordx4 v[120:121], off
	s_mov_b32 m0, s40
	v_lshl_add_u64 v[120:121], s[38:39], 0, v[130:131]
	s_mov_b64 s[38:39], s[36:37]
	global_load_lds_dwordx4 v[120:121], off
	s_mov_b32 m0, s1
	v_lshl_add_u64 v[120:121], s[38:39], 0, v[128:129]
	s_add_u32 s38, s36, 0x80000
	s_addc_u32 s39, s37, 0
	global_load_lds_dwordx4 v[120:121], off
	s_mov_b32 m0, s2
	v_lshl_add_u64 v[120:121], s[38:39], 0, v[128:129]
	global_load_lds_dwordx4 v[120:121], off
	s_waitcnt vmcnt(8)
	s_waitcnt lgkmcnt(0)
	s_barrier
; #define G8_STAGE(bufoff, gbase, NM) do { _Pragma("unroll") for (int _i = 0; _i < 2; ++_i) { \
;     const char* _b = (const char*)(gbase) + (_i ? p2##NM : (size_t)0); asm volatile("" : "+s"(_b));     \
;     __builtin_amdgcn_global_load_lds((const unsigned*)(_b + voff##NM), (LAS unsigned*)(lds + (bufoff) + ldsw + _i * 8192), 16, 0, 0); } } while (0)
; #define G8_WAIT_V(n) asm volatile("s_waitcnt vmcnt(" #n ")" ::: "memory")
; #define G8_WAIT_L(n) asm volatile("s_waitcnt lgkmcnt(" #n ")" ::: "memory")
; #define G8_BAR __builtin_amdgcn_s_barrier()
; #define G8_SCHED __builtin_amdgcn_sched_barrier(0)
;     ...
;       G8_LDA(At, 0, 1); G8_STAGE(G8_SB(0, 0), b2, B); G8_STAGE(G8_SB(0, 1), b2 + hstepB, B); G8_STAGE(G8_SA(0, 0), a2, A);
;       G8_WAIT_V(8); G8_WAIT_L(0); G8_BAR; if (d0a) G8_MMA(1, 0, At, B0); if (d1a) G8_MMA(1, 1, At, B1); G8_BAR; G8_SCHED;
;       G8_LDB(B0, 1, 0); G8_LDB(B1, 1, 1); G8_SCHED; G8_LDA(At, 1, 0); G8_STAGE(G8_SA(0, 1), a2 + hstepA, A);
;       G8_WAIT_V(8); G8_WAIT_L(0); G8_BAR; if (d0b) G8_MMA(0, 0, At, B0); if (d1b) G8_MMA(0, 1, At, B1); G8_BAR; G8_SCHED;
;       G8_LDA(At, 1, 1); G8_STAGE(G8_SB(1, 0), b3, B); G8_STAGE(G8_SB(1, 1), b3 + hstepB, B); G8_STAGE(G8_SA(1, 0), a3, A);
;       G8_WAIT_V(8); G8_WAIT_L(0); G8_BAR; if (d0b) G8_MMA(1, 0, At, B0); if (d1b) G8_MMA(1, 1, At, B1); G8_BAR; G8_SCHED;
;     }
;     if (wr == 0) G8_BAR;
	s_setprio 1
	s_waitcnt lgkmcnt(0)
	v_mfma_f32_16x16x128_f8f6f4 v[178:181], v[16:23], v[48:55], 0
	v_mfma_f32_16x16x128_f8f6f4 v[182:185], v[32:39], v[48:55], 0
	v_mfma_f32_16x16x128_f8f6f4 v[186:189], v[16:23], v[64:71], 0
	v_mfma_f32_16x16x128_f8f6f4 v[190:193], v[32:39], v[64:71], 0
	v_mfma_f32_16x16x128_f8f6f4 v[194:197], v[16:23], v[80:87], 0
	v_mfma_f32_16x16x128_f8f6f4 v[202:205], v[32:39], v[80:87], 0
	v_mfma_f32_16x16x128_f8f6f4 v[206:209], v[16:23], v[96:103], 0
	v_mfma_f32_16x16x128_f8f6f4 v[210:213], v[32:39], v[96:103], 0
	s_setprio 0
	s_barrier
	v_add_u32_e32 v32, s54, v138
	ds_read_b128 v[16:19], v32
	ds_read_b128 v[20:23], v32 offset:1024
	ds_read_b128 v[142:145], v32 offset:2048
	ds_read_b128 v[146:149], v32 offset:3072
	s_add_u32 s38, s36, 0x100000
	s_addc_u32 s39, s37, 0
	s_add_u32 s36, s36, 0x180000
	s_mov_b32 m0, s3
	ds_read_b128 v[32:35], v140 offset:32768
	ds_read_b128 v[36:39], v140 offset:33792
	ds_read_b128 v[48:51], v140 offset:34816
	ds_read_b128 v[52:55], v140 offset:35840
	ds_read_b128 v[64:67], v140 offset:36864
	ds_read_b128 v[68:71], v140 offset:37888
	ds_read_b128 v[150:153], v140 offset:38912
	ds_read_b128 v[154:157], v140 offset:39936
	s_addc_u32 s37, s37, 0
	v_lshl_add_u64 v[80:81], s[38:39], 0, v[128:129]
	global_load_lds_dwordx4 v[80:81], off
	s_mov_b32 m0, s13
	v_lshl_add_u64 v[80:81], s[36:37], 0, v[128:129]
	global_load_lds_dwordx4 v[80:81], off
	s_waitcnt vmcnt(8)
	s_waitcnt lgkmcnt(0)
	s_barrier
	s_setprio 1
	s_waitcnt lgkmcnt(0)
	v_mfma_f32_16x16x128_f8f6f4 v[124:127], v[16:23], v[32:39], v[112:115]
	v_mfma_f32_16x16x128_f8f6f4 v[120:123], v[142:149], v[32:39], v[116:119]
	v_mfma_f32_16x16x128_f8f6f4 v[116:119], v[16:23], v[48:55], v[132:135]
	v_mfma_f32_16x16x128_f8f6f4 v[112:115], v[142:149], v[48:55], v[158:161]
	v_mfma_f32_16x16x128_f8f6f4 v[100:103], v[16:23], v[64:71], v[162:165]
	v_mfma_f32_16x16x128_f8f6f4 v[96:99], v[142:149], v[64:71], v[166:169]
	v_mfma_f32_16x16x128_f8f6f4 v[84:87], v[16:23], v[150:157], v[170:173]
	v_mfma_f32_16x16x128_f8f6f4 v[80:83], v[142:149], v[150:157], v[174:177]
	s_setprio 0
	s_barrier
	s_mov_b64 s[36:37], s[34:35]
	ds_read_b128 v[32:35], v140 offset:49152
	ds_read_b128 v[36:39], v140 offset:50176
	ds_read_b128 v[150:153], v140 offset:51200
	ds_read_b128 v[154:157], v140 offset:52224
	ds_read_b128 v[158:161], v140 offset:53248
	ds_read_b128 v[162:165], v140 offset:54272
	ds_read_b128 v[166:169], v140 offset:55296
	ds_read_b128 v[170:173], v140 offset:56320
	s_mov_b32 m0, s53
	v_lshl_add_u64 v[48:49], s[36:37], 0, v[130:131]
	s_add_u32 s36, s34, 0x8000
	s_addc_u32 s37, s35, 0
	global_load_lds_dwordx4 v[48:49], off
	s_mov_b32 m0, s41
	v_lshl_add_u64 v[48:49], s[36:37], 0, v[130:131]
	s_add_u32 s36, s34, 0x10000
	s_addc_u32 s37, s35, 0
	s_add_u32 s34, s34, 0x18000
	global_load_lds_dwordx4 v[48:49], off
	s_mov_b32 m0, s49
	v_lshl_add_u64 v[48:49], s[36:37], 0, v[130:131]
	s_addc_u32 s35, s35, 0
	global_load_lds_dwordx4 v[48:49], off
	s_mov_b32 m0, s50
	v_lshl_add_u64 v[48:49], s[34:35], 0, v[130:131]
	s_mov_b64 s[34:35], s[30:31]
	s_add_u32 s30, s30, 0x80000
	global_load_lds_dwordx4 v[48:49], off
	s_mov_b32 m0, s29
	v_lshl_add_u64 v[48:49], s[34:35], 0, v[128:129]
	s_addc_u32 s31, s31, 0
	global_load_lds_dwordx4 v[48:49], off
	s_mov_b32 m0, s33
	v_lshl_add_u64 v[48:49], s[30:31], 0, v[128:129]
	global_load_lds_dwordx4 v[48:49], off
	s_waitcnt vmcnt(8)
	s_waitcnt lgkmcnt(0)
	s_barrier
	s_setprio 1
	s_waitcnt lgkmcnt(0)
	v_mfma_f32_16x16x128_f8f6f4 v[68:71], v[16:23], v[32:39], v[178:181]
	v_mfma_f32_16x16x128_f8f6f4 v[64:67], v[142:149], v[32:39], v[182:185]
	v_mfma_f32_16x16x128_f8f6f4 v[52:55], v[16:23], v[150:157], v[186:189]
	v_mfma_f32_16x16x128_f8f6f4 v[48:51], v[142:149], v[150:157], v[190:193]
	v_mfma_f32_16x16x128_f8f6f4 v[36:39], v[16:23], v[158:165], v[194:197]
	v_mfma_f32_16x16x128_f8f6f4 v[32:35], v[142:149], v[158:165], v[202:205]
	v_mfma_f32_16x16x128_f8f6f4 v[20:23], v[16:23], v[166:173], v[206:209]
	v_mfma_f32_16x16x128_f8f6f4 v[16:19], v[142:149], v[166:173], v[210:213]
	s_setprio 0
	s_barrier
	s_andn2_b64 vcc, exec, s[10:11]
	s_cbranch_vccnz .LBB0_1047
	s_barrier

;     ...
; #pragma unroll
;     for (int a = 0; a < 2; ++a)
; #pragma unroll
;       for (int b = 0; b < 2; ++b)
; #pragma unroll
;         for (int m = 0; m < 4; ++m)
; #pragma unroll
;           for (int n = 0; n < 2; ++n) acc[a][b][m][n] = (f32x4){0.f, 0.f, 0.f, 0.f};
;     cur = nxt; cA = nA; cB = nB; ++ui;
.LBB0_1077:
	s_add_u32 s17, s26, 0x100
	v_mov_b32_e32 v0, 0
	s_addc_u32 s23, s27, 0
	s_mov_b32 s47, -2
	v_mov_b32_e32 v1, v0
	v_mov_b32_e32 v2, v0
	v_mov_b32_e32 v3, v0
	v_mov_b32_e32 v4, v0
	v_mov_b32_e32 v5, v0
	v_mov_b32_e32 v6, v0
	v_mov_b32_e32 v7, v0
	v_mov_b32_e32 v16, v0
	v_mov_b32_e32 v17, v0
	v_mov_b32_e32 v18, v0
	v_mov_b32_e32 v19, v0
	v_mov_b32_e32 v20, v0
	v_mov_b32_e32 v21, v0
	v_mov_b32_e32 v22, v0
	v_mov_b32_e32 v23, v0
	v_mov_b32_e32 v32, v0
	v_mov_b32_e32 v33, v0
	v_mov_b32_e32 v34, v0
	v_mov_b32_e32 v35, v0
	v_mov_b32_e32 v36, v0
	v_mov_b32_e32 v37, v0
	v_mov_b32_e32 v38, v0
	v_mov_b32_e32 v39, v0
	v_mov_b32_e32 v48, v0
	v_mov_b32_e32 v49, v0
	v_mov_b32_e32 v50, v0
	v_mov_b32_e32 v51, v0
	v_mov_b32_e32 v52, v0
	v_mov_b32_e32 v53, v0
	v_mov_b32_e32 v54, v0
	v_mov_b32_e32 v55, v0
	v_mov_b32_e32 v8, v0
	v_mov_b32_e32 v9, v0
	v_mov_b32_e32 v10, v0
	v_mov_b32_e32 v11, v0
	v_mov_b32_e32 v12, v0
	v_mov_b32_e32 v13, v0
	v_mov_b32_e32 v14, v0
	v_mov_b32_e32 v15, v0
	v_mov_b32_e32 v24, v0
	v_mov_b32_e32 v25, v0
	v_mov_b32_e32 v26, v0
	v_mov_b32_e32 v27, v0
	v_mov_b32_e32 v28, v0
	v_mov_b32_e32 v29, v0
	v_mov_b32_e32 v30, v0
	v_mov_b32_e32 v31, v0
	v_mov_b32_e32 v40, v0
	v_mov_b32_e32 v41, v0
	v_mov_b32_e32 v42, v0
	v_mov_b32_e32 v43, v0
	v_mov_b32_e32 v44, v0
	v_mov_b32_e32 v45, v0
	v_mov_b32_e32 v46, v0
	v_mov_b32_e32 v47, v0
	v_mov_b32_e32 v56, v0
	v_mov_b32_e32 v57, v0
	v_mov_b32_e32 v58, v0
	v_mov_b32_e32 v59, v0
	v_mov_b32_e32 v60, v0
	v_mov_b32_e32 v61, v0
	v_mov_b32_e32 v62, v0
	v_mov_b32_e32 v63, v0
	v_mov_b32_e32 v64, v0
	v_mov_b32_e32 v65, v0
	v_mov_b32_e32 v66, v0
	v_mov_b32_e32 v67, v0
	v_mov_b32_e32 v68, v0
	v_mov_b32_e32 v69, v0
	v_mov_b32_e32 v70, v0
	v_mov_b32_e32 v71, v0
	v_mov_b32_e32 v80, v0
	v_mov_b32_e32 v81, v0
	v_mov_b32_e32 v82, v0
	v_mov_b32_e32 v83, v0
	v_mov_b32_e32 v84, v0
	v_mov_b32_e32 v85, v0
	v_mov_b32_e32 v86, v0
	v_mov_b32_e32 v87, v0
	v_mov_b32_e32 v96, v0
	v_mov_b32_e32 v97, v0
	v_mov_b32_e32 v98, v0
	v_mov_b32_e32 v99, v0
	v_mov_b32_e32 v100, v0
	v_mov_b32_e32 v101, v0
	v_mov_b32_e32 v102, v0
	v_mov_b32_e32 v103, v0
	v_mov_b32_e32 v112, v0
	v_mov_b32_e32 v113, v0
	v_mov_b32_e32 v114, v0
	v_mov_b32_e32 v115, v0
	v_mov_b32_e32 v116, v0
	v_mov_b32_e32 v117, v0
	v_mov_b32_e32 v118, v0
	v_mov_b32_e32 v119, v0
	v_mov_b32_e32 v72, v0
	v_mov_b32_e32 v73, v0
	v_mov_b32_e32 v74, v0
	v_mov_b32_e32 v75, v0
	v_mov_b32_e32 v76, v0
	v_mov_b32_e32 v77, v0
	v_mov_b32_e32 v78, v0
	v_mov_b32_e32 v79, v0
	v_mov_b32_e32 v88, v0
	v_mov_b32_e32 v89, v0
	v_mov_b32_e32 v90, v0
	v_mov_b32_e32 v91, v0
	v_mov_b32_e32 v92, v0
	v_mov_b32_e32 v93, v0
	v_mov_b32_e32 v94, v0
	v_mov_b32_e32 v95, v0
	v_mov_b32_e32 v104, v0
	v_mov_b32_e32 v105, v0
	v_mov_b32_e32 v106, v0
	v_mov_b32_e32 v107, v0
	v_mov_b32_e32 v108, v0
	v_mov_b32_e32 v109, v0
	v_mov_b32_e32 v110, v0
	v_mov_b32_e32 v111, v0
	v_mov_b32_e32 v120, v0
	v_mov_b32_e32 v121, v0
	v_mov_b32_e32 v122, v0
	v_mov_b32_e32 v123, v0
	v_mov_b32_e32 v124, v0
	v_mov_b32_e32 v125, v0
	v_mov_b32_e32 v126, v0
	v_mov_b32_e32 v127, v0

;     ...
; #pragma unroll
;     for (int a = 0; a < 2; ++a)
; #pragma unroll
;       for (int b = 0; b < 2; ++b)
; #pragma unroll
;         for (int m = 0; m < 4; ++m)
; #pragma unroll
;           for (int n = 0; n < 2; ++n) acc[a][b][m][n] = (f32x4){0.f, 0.f, 0.f, 0.f};
;     cur = nxt; cA = nA; cB = nB; ++ui;
.LBB0_1124:
	s_add_u32 s50, s4, 0x100
	s_addc_u32 s51, s5, 0
	s_add_u32 s52, s26, 0x100
	s_addc_u32 s53, s27, 0
	s_add_u32 s4, s4, 0x84080
	v_mov_b32_e32 v0, 0
	s_addc_u32 s5, s5, 0
	s_mov_b32 s54, -2
	v_mov_b32_e32 v1, v0
	v_mov_b32_e32 v2, v0
	v_mov_b32_e32 v3, v0
	v_mov_b32_e32 v4, v0
	v_mov_b32_e32 v5, v0
	v_mov_b32_e32 v6, v0
	v_mov_b32_e32 v7, v0
	v_mov_b32_e32 v16, v0
	v_mov_b32_e32 v17, v0
	v_mov_b32_e32 v18, v0
	v_mov_b32_e32 v19, v0
	v_mov_b32_e32 v20, v0
	v_mov_b32_e32 v21, v0
	v_mov_b32_e32 v22, v0
	v_mov_b32_e32 v23, v0
	v_mov_b32_e32 v32, v0
	v_mov_b32_e32 v33, v0
	v_mov_b32_e32 v34, v0
	v_mov_b32_e32 v35, v0
	v_mov_b32_e32 v36, v0
	v_mov_b32_e32 v37, v0
	v_mov_b32_e32 v38, v0
	v_mov_b32_e32 v39, v0
	v_mov_b32_e32 v48, v0
	v_mov_b32_e32 v49, v0
	v_mov_b32_e32 v50, v0
	v_mov_b32_e32 v51, v0
	v_mov_b32_e32 v52, v0
	v_mov_b32_e32 v53, v0
	v_mov_b32_e32 v54, v0
	v_mov_b32_e32 v55, v0
	v_mov_b32_e32 v8, v0
	v_mov_b32_e32 v9, v0
	v_mov_b32_e32 v10, v0
	v_mov_b32_e32 v11, v0
	v_mov_b32_e32 v12, v0
	v_mov_b32_e32 v13, v0
	v_mov_b32_e32 v14, v0
	v_mov_b32_e32 v15, v0
	v_mov_b32_e32 v24, v0
	v_mov_b32_e32 v25, v0
	v_mov_b32_e32 v26, v0
	v_mov_b32_e32 v27, v0
	v_mov_b32_e32 v28, v0
	v_mov_b32_e32 v29, v0
	v_mov_b32_e32 v30, v0
	v_mov_b32_e32 v31, v0
	v_mov_b32_e32 v40, v0
	v_mov_b32_e32 v41, v0
	v_mov_b32_e32 v42, v0
	v_mov_b32_e32 v43, v0
	v_mov_b32_e32 v44, v0
	v_mov_b32_e32 v45, v0
	v_mov_b32_e32 v46, v0
	v_mov_b32_e32 v47, v0
	v_mov_b32_e32 v56, v0
	v_mov_b32_e32 v57, v0
	v_mov_b32_e32 v58, v0
	v_mov_b32_e32 v59, v0
	v_mov_b32_e32 v60, v0
	v_mov_b32_e32 v61, v0
	v_mov_b32_e32 v62, v0
	v_mov_b32_e32 v63, v0
	v_mov_b32_e32 v64, v0
	v_mov_b32_e32 v65, v0
	v_mov_b32_e32 v66, v0
	v_mov_b32_e32 v67, v0
	v_mov_b32_e32 v68, v0
	v_mov_b32_e32 v69, v0
	v_mov_b32_e32 v70, v0
	v_mov_b32_e32 v71, v0
	v_mov_b32_e32 v80, v0
	v_mov_b32_e32 v81, v0
	v_mov_b32_e32 v82, v0
	v_mov_b32_e32 v83, v0
	v_mov_b32_e32 v84, v0
	v_mov_b32_e32 v85, v0
	v_mov_b32_e32 v86, v0
	v_mov_b32_e32 v87, v0
	v_mov_b32_e32 v96, v0
	v_mov_b32_e32 v97, v0
	v_mov_b32_e32 v98, v0
	v_mov_b32_e32 v99, v0
	v_mov_b32_e32 v100, v0
	v_mov_b32_e32 v101, v0
	v_mov_b32_e32 v102, v0
	v_mov_b32_e32 v103, v0
	v_mov_b32_e32 v112, v0
	v_mov_b32_e32 v113, v0
	v_mov_b32_e32 v114, v0
	v_mov_b32_e32 v115, v0
	v_mov_b32_e32 v116, v0
	v_mov_b32_e32 v117, v0
	v_mov_b32_e32 v118, v0
	v_mov_b32_e32 v119, v0
	v_mov_b32_e32 v72, v0
	v_mov_b32_e32 v73, v0
	v_mov_b32_e32 v74, v0
	v_mov_b32_e32 v75, v0
	v_mov_b32_e32 v76, v0
	v_mov_b32_e32 v77, v0
	v_mov_b32_e32 v78, v0
	v_mov_b32_e32 v79, v0
	v_mov_b32_e32 v88, v0
	v_mov_b32_e32 v89, v0
	v_mov_b32_e32 v90, v0
	v_mov_b32_e32 v91, v0
	v_mov_b32_e32 v92, v0
	v_mov_b32_e32 v93, v0
	v_mov_b32_e32 v94, v0
	v_mov_b32_e32 v95, v0
	v_mov_b32_e32 v104, v0
	v_mov_b32_e32 v105, v0
	v_mov_b32_e32 v106, v0
	v_mov_b32_e32 v107, v0
	v_mov_b32_e32 v108, v0
	v_mov_b32_e32 v109, v0
	v_mov_b32_e32 v110, v0
	v_mov_b32_e32 v111, v0
	v_mov_b32_e32 v120, v0
	v_mov_b32_e32 v121, v0
	v_mov_b32_e32 v122, v0
	v_mov_b32_e32 v123, v0
	v_mov_b32_e32 v124, v0
	v_mov_b32_e32 v125, v0
	v_mov_b32_e32 v126, v0
	v_mov_b32_e32 v127, v0

;     ...
; #pragma unroll
;     for (int a = 0; a < 2; ++a)
; #pragma unroll
;       for (int b = 0; b < 2; ++b)
; #pragma unroll
;         for (int m = 0; m < 4; ++m)
; #pragma unroll
;           for (int n = 0; n < 2; ++n) acc[a][b][m][n] = (f32x4){0.f, 0.f, 0.f, 0.f};
;     cur = nxt; cA = nA; cB = nB; ++ui;
.LBB0_1214:
	s_add_u32 s11, s20, 0x100
	v_mov_b32_e32 v0, 0
	s_addc_u32 s17, s21, 0
	s_mov_b32 s42, -2
	v_mov_b32_e32 v1, v0
	v_mov_b32_e32 v2, v0
	v_mov_b32_e32 v3, v0
	v_mov_b32_e32 v4, v0
	v_mov_b32_e32 v5, v0
	v_mov_b32_e32 v6, v0
	v_mov_b32_e32 v7, v0
	v_mov_b32_e32 v16, v0
	v_mov_b32_e32 v17, v0
	v_mov_b32_e32 v18, v0
	v_mov_b32_e32 v19, v0
	v_mov_b32_e32 v20, v0
	v_mov_b32_e32 v21, v0
	v_mov_b32_e32 v22, v0
	v_mov_b32_e32 v23, v0
	v_mov_b32_e32 v32, v0
	v_mov_b32_e32 v33, v0
	v_mov_b32_e32 v34, v0
	v_mov_b32_e32 v35, v0
	v_mov_b32_e32 v36, v0
	v_mov_b32_e32 v37, v0
	v_mov_b32_e32 v38, v0
	v_mov_b32_e32 v39, v0
	v_mov_b32_e32 v48, v0
	v_mov_b32_e32 v49, v0
	v_mov_b32_e32 v50, v0
	v_mov_b32_e32 v51, v0
	v_mov_b32_e32 v52, v0
	v_mov_b32_e32 v53, v0
	v_mov_b32_e32 v54, v0
	v_mov_b32_e32 v55, v0
	v_mov_b32_e32 v8, v0
	v_mov_b32_e32 v9, v0
	v_mov_b32_e32 v10, v0
	v_mov_b32_e32 v11, v0
	v_mov_b32_e32 v12, v0
	v_mov_b32_e32 v13, v0
	v_mov_b32_e32 v14, v0
	v_mov_b32_e32 v15, v0
	v_mov_b32_e32 v24, v0
	v_mov_b32_e32 v25, v0
	v_mov_b32_e32 v26, v0
	v_mov_b32_e32 v27, v0
	v_mov_b32_e32 v28, v0
	v_mov_b32_e32 v29, v0
	v_mov_b32_e32 v30, v0
	v_mov_b32_e32 v31, v0
	v_mov_b32_e32 v40, v0
	v_mov_b32_e32 v41, v0
	v_mov_b32_e32 v42, v0
	v_mov_b32_e32 v43, v0
	v_mov_b32_e32 v44, v0
	v_mov_b32_e32 v45, v0
	v_mov_b32_e32 v46, v0
	v_mov_b32_e32 v47, v0
	v_mov_b32_e32 v56, v0
	v_mov_b32_e32 v57, v0
	v_mov_b32_e32 v58, v0
	v_mov_b32_e32 v59, v0
	v_mov_b32_e32 v60, v0
	v_mov_b32_e32 v61, v0
	v_mov_b32_e32 v62, v0
	v_mov_b32_e32 v63, v0
	v_mov_b32_e32 v64, v0
	v_mov_b32_e32 v65, v0
	v_mov_b32_e32 v66, v0
	v_mov_b32_e32 v67, v0
	v_mov_b32_e32 v68, v0
	v_mov_b32_e32 v69, v0
	v_mov_b32_e32 v70, v0
	v_mov_b32_e32 v71, v0
	v_mov_b32_e32 v80, v0
	v_mov_b32_e32 v81, v0
	v_mov_b32_e32 v82, v0
	v_mov_b32_e32 v83, v0
	v_mov_b32_e32 v84, v0
	v_mov_b32_e32 v85, v0
	v_mov_b32_e32 v86, v0
	v_mov_b32_e32 v87, v0
	v_mov_b32_e32 v96, v0
	v_mov_b32_e32 v97, v0
	v_mov_b32_e32 v98, v0
	v_mov_b32_e32 v99, v0
	v_mov_b32_e32 v100, v0
	v_mov_b32_e32 v101, v0
	v_mov_b32_e32 v102, v0
	v_mov_b32_e32 v103, v0
	v_mov_b32_e32 v112, v0
	v_mov_b32_e32 v113, v0
	v_mov_b32_e32 v114, v0
	v_mov_b32_e32 v115, v0
	v_mov_b32_e32 v116, v0
	v_mov_b32_e32 v117, v0
	v_mov_b32_e32 v118, v0
	v_mov_b32_e32 v119, v0
	v_mov_b32_e32 v72, v0
	v_mov_b32_e32 v73, v0
	v_mov_b32_e32 v74, v0
	v_mov_b32_e32 v75, v0
	v_mov_b32_e32 v76, v0
	v_mov_b32_e32 v77, v0
	v_mov_b32_e32 v78, v0
	v_mov_b32_e32 v79, v0
	v_mov_b32_e32 v88, v0
	v_mov_b32_e32 v89, v0
	v_mov_b32_e32 v90, v0
	v_mov_b32_e32 v91, v0
	v_mov_b32_e32 v92, v0
	v_mov_b32_e32 v93, v0
	v_mov_b32_e32 v94, v0
	v_mov_b32_e32 v95, v0
	v_mov_b32_e32 v104, v0
	v_mov_b32_e32 v105, v0
	v_mov_b32_e32 v106, v0
	v_mov_b32_e32 v107, v0
	v_mov_b32_e32 v108, v0
	v_mov_b32_e32 v109, v0
	v_mov_b32_e32 v110, v0
	v_mov_b32_e32 v111, v0
	v_mov_b32_e32 v120, v0
	v_mov_b32_e32 v121, v0
	v_mov_b32_e32 v122, v0
	v_mov_b32_e32 v123, v0
	v_mov_b32_e32 v124, v0
	v_mov_b32_e32 v125, v0
	v_mov_b32_e32 v126, v0
	v_mov_b32_e32 v127, v0
